# select_rows all-pairs rank loop unrolled by two (two readlane/compare/add-carry chains per trip)
# speedup vs baseline: 1.0069x; 1.0069x over previous
; #define WL1(J) if constexpr (J < NJ) { const unsigned long long w_ = __ballot(key[J] >= tau); const unsigned wl_ = (unsigned)w_, wh_ = (unsigned)(w_ >> 32); \
;                 asm volatile("s_nop 3\n\tv_writelane_b32 %0, %2, " #J "\n\tv_writelane_b32 %1, %3, " #J : "+v"(mlo), "+v"(mhi) : "s"(wl_), "s"(wh_)); }
; template <int NJ>
; __device__ __forceinline__ void select_rows(const GAS float* sr0, GAS unsigned long long* mb0, LAS unsigned* hist, LAS unsigned* kbuf, int ntl, int lane) {
;     ...
;             for (unsigned i = 0; i < C; ++i) { const unsigned o = (unsigned)__builtin_amdgcn_readlane((int)mykey, (int)i); cgt += (o > mykey) ? 1u : 0u; }
;             unsigned t = (have && cgt < rem) ? mykey : 0xffffffffu;
; #pragma unroll
;             for (int o = 1; o < 64; o <<= 1) t = min(t, (unsigned)__shfl_xor((int)t, o));
;             tau = t;
;             const unsigned long long eqm = __ballot(have && mykey == tau);
;             cnteq = (unsigned)__popcll(eqm);
;             remf = rem - (unsigned)__builtin_amdgcn_readlane((int)cgt, eqm ? (int)__builtin_ctzll(eqm) : 0);
;             generic = cnteq > remf;
;         }
;         unsigned mlo = 0u, mhi = 0u;
;         if (!generic) {
;     ...
;             WL1(0) WL1(1) WL1(2) WL1(3) WL1(4) WL1(5) WL1(6) WL1(7) WL1(8) WL1(9) WL1(10) WL1(11) WL1(12) WL1(13) WL1(14) WL1(15)
;             WL1(16) WL1(17) WL1(18) WL1(19) WL1(20) WL1(21) WL1(22) WL1(23) WL1(24) WL1(25) WL1(26) WL1(27) WL1(28) WL1(29) WL1(30) WL1(31)
.Lrk1_top:
	s_add_i32 s98, s2, 1
	s_cmp_lt_u32 s98, s9
	s_cbranch_scc0 .Lrk1_one
	v_readlane_b32 s0, v2, s2
	v_readlane_b32 s98, v2, s98
	s_add_i32 s2, s2, 2
	v_cmp_gt_u32_e64 s[0:1], s0, v2
	v_cmp_gt_u32_e64 s[98:99], s98, v2
	s_cmp_lt_u32 s2, s9
	v_addc_co_u32_e64 v3, s[0:1], 0, v3, s[0:1]
	v_addc_co_u32_e64 v3, s[98:99], 0, v3, s[98:99]
	s_cbranch_scc1 .Lrk1_top
	s_branch .Lrk1_done
.Lrk1_one:
	v_readlane_b32 s0, v2, s2
	s_add_i32 s2, s2, 1
	s_nop 1
	v_cmp_gt_u32_e64 s[0:1], s0, v2
	s_nop 1
	v_addc_co_u32_e64 v3, s[0:1], 0, v3, s[0:1]
.Lrk1_done:
.LBB0_521:
	s_sub_i32 s2, 0x100, s8
	v_cmp_gt_u32_e64 s[0:1], s2, v3
	v_and_b32_e32 v45, 64, v224
	s_and_b64 s[0:1], vcc, s[0:1]
	v_add_u32_e32 v45, 64, v45
	v_xor_b32_e32 v46, 1, v224
	s_waitcnt lgkmcnt(0)
	v_cndmask_b32_e64 v5, -1, v2, s[0:1]
	s_nop 1
	v_min_u32_dpp v5, v5, v5 row_shr:1 row_mask:0xf bank_mask:0xf
	s_nop 1
	v_min_u32_dpp v5, v5, v5 row_shr:2 row_mask:0xf bank_mask:0xf
	s_nop 1
	v_min_u32_dpp v5, v5, v5 row_shr:4 row_mask:0xf bank_mask:0xf
	s_nop 1
	v_min_u32_dpp v5, v5, v5 row_shr:8 row_mask:0xf bank_mask:0xf
	s_nop 1
	v_min_u32_dpp v5, v5, v5 row_bcast:15 row_mask:0xa bank_mask:0xf
	s_nop 1
	v_min_u32_dpp v5, v5, v5 row_bcast:31 row_mask:0xc bank_mask:0xf
	s_nop 1
	v_readlane_b32 s0, v5, 63
	s_nop 1
	v_mov_b32_e32 v5, s0
	v_cmp_eq_u32_e64 s[0:1], v2, v5
	s_and_b64 s[0:1], vcc, s[0:1]
	s_nop 0
	v_cndmask_b32_e64 v2, 0, 1, s[0:1]
	v_cmp_ne_u32_e32 vcc, 0, v2
	s_bcnt1_i32_b64 s0, vcc
	s_ff1_i32_b64 s1, vcc
	s_cmp_lg_u64 vcc, 0
	s_cselect_b32 s1, s1, 0
	v_readlane_b32 s1, v3, s1
	s_sub_i32 s1, s2, s1
	s_cmp_ge_u32 s1, s0
	s_mov_b64 s[0:1], -1
	s_cbranch_scc0 .LBB0_523
	v_cmp_ge_u32_e32 vcc, v4, v5
	v_mov_b32_e32 v2, v0
	v_mov_b32_e32 v3, v0
	s_nop 3
	v_writelane_b32 v2, vcc_lo, 0
	v_writelane_b32 v3, vcc_hi, 0
	v_cmp_ge_u32_e32 vcc, v10, v5
	s_nop 3
	v_writelane_b32 v2, vcc_lo, 1
	v_writelane_b32 v3, vcc_hi, 1
	v_cmp_ge_u32_e32 vcc, v11, v5
	s_nop 3
	v_writelane_b32 v2, vcc_lo, 2
	v_writelane_b32 v3, vcc_hi, 2
	v_cmp_ge_u32_e32 vcc, v12, v5
	s_nop 3
	v_writelane_b32 v2, vcc_lo, 3
	v_writelane_b32 v3, vcc_hi, 3
	v_cmp_ge_u32_e32 vcc, v13, v5
	s_nop 3
	v_writelane_b32 v2, vcc_lo, 4
	v_writelane_b32 v3, vcc_hi, 4
	v_cmp_ge_u32_e32 vcc, v14, v5
	s_nop 3
	v_writelane_b32 v2, vcc_lo, 5
	v_writelane_b32 v3, vcc_hi, 5
	v_cmp_ge_u32_e32 vcc, v15, v5
	s_nop 3
	v_writelane_b32 v2, vcc_lo, 6
	v_writelane_b32 v3, vcc_hi, 6
	v_cmp_ge_u32_e32 vcc, v16, v5
	s_nop 3
	v_writelane_b32 v2, vcc_lo, 7
	v_writelane_b32 v3, vcc_hi, 7
	v_cmp_ge_u32_e32 vcc, v17, v5
	s_nop 3
	v_writelane_b32 v2, vcc_lo, 8
	v_writelane_b32 v3, vcc_hi, 8
	v_cmp_ge_u32_e32 vcc, v18, v5
	s_nop 3
	v_writelane_b32 v2, vcc_lo, 9
	v_writelane_b32 v3, vcc_hi, 9
	v_cmp_ge_u32_e32 vcc, v19, v5
	s_nop 3
	v_writelane_b32 v2, vcc_lo, 10
	v_writelane_b32 v3, vcc_hi, 10
	v_cmp_ge_u32_e32 vcc, v20, v5
	s_nop 3
	v_writelane_b32 v2, vcc_lo, 11
	v_writelane_b32 v3, vcc_hi, 11
	v_cmp_ge_u32_e32 vcc, v21, v5
	s_nop 3
	v_writelane_b32 v2, vcc_lo, 12
	v_writelane_b32 v3, vcc_hi, 12
	v_cmp_ge_u32_e32 vcc, v22, v5
	s_nop 3
	v_writelane_b32 v2, vcc_lo, 13
	v_writelane_b32 v3, vcc_hi, 13
	v_cmp_ge_u32_e32 vcc, v23, v5
	s_nop 3
	v_writelane_b32 v2, vcc_lo, 14
	v_writelane_b32 v3, vcc_hi, 14
	v_cmp_ge_u32_e32 vcc, v24, v5
	s_nop 3
	v_writelane_b32 v2, vcc_lo, 15
	v_writelane_b32 v3, vcc_hi, 15
	v_cmp_ge_u32_e32 vcc, v25, v5
	s_nop 3
	v_writelane_b32 v2, vcc_lo, 16
	v_writelane_b32 v3, vcc_hi, 16
	v_cmp_ge_u32_e32 vcc, v26, v5
	s_nop 3
	v_writelane_b32 v2, vcc_lo, 17
	v_writelane_b32 v3, vcc_hi, 17
	v_cmp_ge_u32_e32 vcc, v27, v5
	s_nop 3
	v_writelane_b32 v2, vcc_lo, 18
	v_writelane_b32 v3, vcc_hi, 18
	v_cmp_ge_u32_e32 vcc, v28, v5
	s_nop 3
	v_writelane_b32 v2, vcc_lo, 19
	v_writelane_b32 v3, vcc_hi, 19
	v_cmp_ge_u32_e32 vcc, v29, v5
	s_nop 3
	v_writelane_b32 v2, vcc_lo, 20
	v_writelane_b32 v3, vcc_hi, 20
	v_cmp_ge_u32_e32 vcc, v30, v5
	s_nop 3
	v_writelane_b32 v2, vcc_lo, 21
	v_writelane_b32 v3, vcc_hi, 21
	v_cmp_ge_u32_e32 vcc, v31, v5
	s_nop 3
	v_writelane_b32 v2, vcc_lo, 22
	v_writelane_b32 v3, vcc_hi, 22
	v_cmp_ge_u32_e32 vcc, v32, v5
	s_nop 3
	v_writelane_b32 v2, vcc_lo, 23
	v_writelane_b32 v3, vcc_hi, 23
	v_cmp_ge_u32_e32 vcc, v33, v5
	s_nop 3
	v_writelane_b32 v2, vcc_lo, 24
	v_writelane_b32 v3, vcc_hi, 24
	v_cmp_ge_u32_e32 vcc, v34, v5
	s_nop 3
	v_writelane_b32 v2, vcc_lo, 25
	v_writelane_b32 v3, vcc_hi, 25
	v_cmp_ge_u32_e32 vcc, v35, v5
	s_nop 3
	v_writelane_b32 v2, vcc_lo, 26
	v_writelane_b32 v3, vcc_hi, 26
	v_cmp_ge_u32_e32 vcc, v36, v5
	s_nop 3
	v_writelane_b32 v2, vcc_lo, 27
	v_writelane_b32 v3, vcc_hi, 27
	v_cmp_ge_u32_e32 vcc, v37, v5
	s_nop 3
	v_writelane_b32 v2, vcc_lo, 28
	v_writelane_b32 v3, vcc_hi, 28
	v_cmp_ge_u32_e32 vcc, v42, v5
	s_nop 3
	v_writelane_b32 v2, vcc_lo, 29
	v_writelane_b32 v3, vcc_hi, 29
	v_cmp_ge_u32_e32 vcc, v43, v5
	s_nop 3
	v_writelane_b32 v2, vcc_lo, 30
	v_writelane_b32 v3, vcc_hi, 30
	v_cmp_ge_u32_e32 vcc, v44, v5
	s_mov_b64 s[0:1], 0
	s_nop 3
	v_writelane_b32 v2, vcc_lo, 31
	v_writelane_b32 v3, vcc_hi, 31

; template <int NJ>
; __device__ __forceinline__ void select_rows(const GAS float* sr0, GAS unsigned long long* mb0, LAS unsigned* hist, LAS unsigned* kbuf, int ntl, int lane) {
;     ...
;             for (unsigned i = 0; i < C; ++i) { const unsigned o = (unsigned)__builtin_amdgcn_readlane((int)mykey, (int)i); cgt += (o > mykey) ? 1u : 0u; }
.Lrk2_top:
	s_add_i32 s98, s2, 1
	s_cmp_lt_u32 s98, s55
	s_cbranch_scc0 .Lrk2_one
	v_readlane_b32 s0, v2, s2
	v_readlane_b32 s98, v2, s98
	s_add_i32 s2, s2, 2
	v_cmp_gt_u32_e64 s[0:1], s0, v2
	v_cmp_gt_u32_e64 s[98:99], s98, v2
	s_cmp_lt_u32 s2, s55
	v_addc_co_u32_e64 v3, s[0:1], 0, v3, s[0:1]
	v_addc_co_u32_e64 v3, s[98:99], 0, v3, s[98:99]
	s_cbranch_scc1 .Lrk2_top
	s_branch .Lrk2_done

; #define WL1(J) if constexpr (J < NJ) { const unsigned long long w_ = __ballot(key[J] >= tau); const unsigned wl_ = (unsigned)w_, wh_ = (unsigned)(w_ >> 32); \
;                 asm volatile("s_nop 3\n\tv_writelane_b32 %0, %2, " #J "\n\tv_writelane_b32 %1, %3, " #J : "+v"(mlo), "+v"(mhi) : "s"(wl_), "s"(wh_)); }
; template <int NJ>
; __device__ __forceinline__ void select_rows(const GAS float* sr0, GAS unsigned long long* mb0, LAS unsigned* hist, LAS unsigned* kbuf, int ntl, int lane) {
;     ...
;             for (unsigned i = 0; i < C; ++i) { const unsigned o = (unsigned)__builtin_amdgcn_readlane((int)mykey, (int)i); cgt += (o > mykey) ? 1u : 0u; }
;             unsigned t = (have && cgt < rem) ? mykey : 0xffffffffu;
; #pragma unroll
;             for (int o = 1; o < 64; o <<= 1) t = min(t, (unsigned)__shfl_xor((int)t, o));
;             tau = t;
;             const unsigned long long eqm = __ballot(have && mykey == tau);
;             cnteq = (unsigned)__popcll(eqm);
;             remf = rem - (unsigned)__builtin_amdgcn_readlane((int)cgt, eqm ? (int)__builtin_ctzll(eqm) : 0);
;             generic = cnteq > remf;
;         }
;         unsigned mlo = 0u, mhi = 0u;
;         if (!generic) {
;     ...
;             WL1(0) WL1(1) WL1(2) WL1(3) WL1(4) WL1(5) WL1(6) WL1(7) WL1(8) WL1(9) WL1(10) WL1(11) WL1(12) WL1(13) WL1(14) WL1(15)
;             WL1(16) WL1(17) WL1(18) WL1(19) WL1(20) WL1(21) WL1(22) WL1(23) WL1(24) WL1(25) WL1(26) WL1(27) WL1(28) WL1(29) WL1(30) WL1(31)
.Lrk2_done:
.LBB0_640:
	s_sub_i32 s2, 0x100, s54
	v_cmp_gt_u32_e64 s[0:1], s2, v3
	v_and_b32_e32 v33, 64, v224
	s_and_b64 s[0:1], vcc, s[0:1]
	v_add_u32_e32 v33, 64, v33
	v_xor_b32_e32 v34, 1, v224
	s_waitcnt lgkmcnt(0)
	v_cndmask_b32_e64 v5, -1, v2, s[0:1]
	s_nop 1
	v_min_u32_dpp v5, v5, v5 row_shr:1 row_mask:0xf bank_mask:0xf
	s_nop 1
	v_min_u32_dpp v5, v5, v5 row_shr:2 row_mask:0xf bank_mask:0xf
	s_nop 1
	v_min_u32_dpp v5, v5, v5 row_shr:4 row_mask:0xf bank_mask:0xf
	s_nop 1
	v_min_u32_dpp v5, v5, v5 row_shr:8 row_mask:0xf bank_mask:0xf
	s_nop 1
	v_min_u32_dpp v5, v5, v5 row_bcast:15 row_mask:0xa bank_mask:0xf
	s_nop 1
	v_min_u32_dpp v5, v5, v5 row_bcast:31 row_mask:0xc bank_mask:0xf
	s_nop 1
	v_readlane_b32 s0, v5, 63
	s_nop 1
	v_mov_b32_e32 v5, s0
	v_cmp_eq_u32_e64 s[0:1], v2, v5
	s_and_b64 s[0:1], vcc, s[0:1]
	s_nop 0
	v_cndmask_b32_e64 v2, 0, 1, s[0:1]
	v_cmp_ne_u32_e32 vcc, 0, v2
	s_bcnt1_i32_b64 s0, vcc
	s_ff1_i32_b64 s1, vcc
	s_cmp_lg_u64 vcc, 0
	s_cselect_b32 s1, s1, 0
	v_readlane_b32 s1, v3, s1
	s_sub_i32 s1, s2, s1
	s_cmp_ge_u32 s1, s0
	s_mov_b64 s[0:1], -1
	s_cbranch_scc0 .LBB0_642
	v_cmp_ge_u32_e32 vcc, v4, v5
	v_mov_b32_e32 v2, v0
	v_mov_b32_e32 v3, v0
	s_nop 3
	v_writelane_b32 v2, vcc_lo, 0
	v_writelane_b32 v3, vcc_hi, 0
	v_cmp_ge_u32_e32 vcc, v10, v5
	s_nop 3
	v_writelane_b32 v2, vcc_lo, 1
	v_writelane_b32 v3, vcc_hi, 1
	v_cmp_ge_u32_e32 vcc, v11, v5
	s_nop 3
	v_writelane_b32 v2, vcc_lo, 2
	v_writelane_b32 v3, vcc_hi, 2
	v_cmp_ge_u32_e32 vcc, v12, v5
	s_nop 3
	v_writelane_b32 v2, vcc_lo, 3
	v_writelane_b32 v3, vcc_hi, 3
	v_cmp_ge_u32_e32 vcc, v13, v5
	s_nop 3
	v_writelane_b32 v2, vcc_lo, 4
	v_writelane_b32 v3, vcc_hi, 4
	v_cmp_ge_u32_e32 vcc, v14, v5
	s_nop 3
	v_writelane_b32 v2, vcc_lo, 5
	v_writelane_b32 v3, vcc_hi, 5
	v_cmp_ge_u32_e32 vcc, v15, v5
	s_nop 3
	v_writelane_b32 v2, vcc_lo, 6
	v_writelane_b32 v3, vcc_hi, 6
	v_cmp_ge_u32_e32 vcc, v16, v5
	s_nop 3
	v_writelane_b32 v2, vcc_lo, 7
	v_writelane_b32 v3, vcc_hi, 7
	v_cmp_ge_u32_e32 vcc, v17, v5
	s_nop 3
	v_writelane_b32 v2, vcc_lo, 8
	v_writelane_b32 v3, vcc_hi, 8
	v_cmp_ge_u32_e32 vcc, v18, v5
	s_nop 3
	v_writelane_b32 v2, vcc_lo, 9
	v_writelane_b32 v3, vcc_hi, 9
	v_cmp_ge_u32_e32 vcc, v19, v5
	s_nop 3
	v_writelane_b32 v2, vcc_lo, 10
	v_writelane_b32 v3, vcc_hi, 10
	v_cmp_ge_u32_e32 vcc, v20, v5
	s_nop 3
	v_writelane_b32 v2, vcc_lo, 11
	v_writelane_b32 v3, vcc_hi, 11
	v_cmp_ge_u32_e32 vcc, v21, v5
	s_nop 3
	v_writelane_b32 v2, vcc_lo, 12
	v_writelane_b32 v3, vcc_hi, 12
	v_cmp_ge_u32_e32 vcc, v22, v5
	s_nop 3
	v_writelane_b32 v2, vcc_lo, 13
	v_writelane_b32 v3, vcc_hi, 13
	v_cmp_ge_u32_e32 vcc, v23, v5
	s_nop 3
	v_writelane_b32 v2, vcc_lo, 14
	v_writelane_b32 v3, vcc_hi, 14
	v_cmp_ge_u32_e32 vcc, v24, v5
	s_nop 3
	v_writelane_b32 v2, vcc_lo, 15
	v_writelane_b32 v3, vcc_hi, 15
	v_cmp_ge_u32_e32 vcc, v25, v5
	s_nop 3
	v_writelane_b32 v2, vcc_lo, 16
	v_writelane_b32 v3, vcc_hi, 16
	v_cmp_ge_u32_e32 vcc, v26, v5
	s_nop 3
	v_writelane_b32 v2, vcc_lo, 17
	v_writelane_b32 v3, vcc_hi, 17
	v_cmp_ge_u32_e32 vcc, v27, v5
	s_nop 3
	v_writelane_b32 v2, vcc_lo, 18
	v_writelane_b32 v3, vcc_hi, 18
	v_cmp_ge_u32_e32 vcc, v28, v5
	s_nop 3
	v_writelane_b32 v2, vcc_lo, 19
	v_writelane_b32 v3, vcc_hi, 19
	v_cmp_ge_u32_e32 vcc, v29, v5
	s_nop 3
	v_writelane_b32 v2, vcc_lo, 20
	v_writelane_b32 v3, vcc_hi, 20
	v_cmp_ge_u32_e32 vcc, v30, v5
	s_nop 3
	v_writelane_b32 v2, vcc_lo, 21
	v_writelane_b32 v3, vcc_hi, 21
	v_cmp_ge_u32_e32 vcc, v31, v5
	s_nop 3
	v_writelane_b32 v2, vcc_lo, 22
	v_writelane_b32 v3, vcc_hi, 22
	v_cmp_ge_u32_e32 vcc, v32, v5
	s_nop 3
	v_writelane_b32 v2, vcc_lo, 23
	v_writelane_b32 v3, vcc_hi, 23
	s_mov_b64 s[0:1], 0

; #define WL1(J) if constexpr (J < NJ) { const unsigned long long w_ = __ballot(key[J] >= tau); const unsigned wl_ = (unsigned)w_, wh_ = (unsigned)(w_ >> 32); \
;                 asm volatile("s_nop 3\n\tv_writelane_b32 %0, %2, " #J "\n\tv_writelane_b32 %1, %3, " #J : "+v"(mlo), "+v"(mhi) : "s"(wl_), "s"(wh_)); }
; template <int NJ>
; __device__ __forceinline__ void select_rows(const GAS float* sr0, GAS unsigned long long* mb0, LAS unsigned* hist, LAS unsigned* kbuf, int ntl, int lane) {
;     ...
;             for (unsigned i = 0; i < C; ++i) { const unsigned o = (unsigned)__builtin_amdgcn_readlane((int)mykey, (int)i); cgt += (o > mykey) ? 1u : 0u; }
;             unsigned t = (have && cgt < rem) ? mykey : 0xffffffffu;
; #pragma unroll
;             for (int o = 1; o < 64; o <<= 1) t = min(t, (unsigned)__shfl_xor((int)t, o));
;             tau = t;
;             const unsigned long long eqm = __ballot(have && mykey == tau);
;             cnteq = (unsigned)__popcll(eqm);
;             remf = rem - (unsigned)__builtin_amdgcn_readlane((int)cgt, eqm ? (int)__builtin_ctzll(eqm) : 0);
;             generic = cnteq > remf;
;         }
;         unsigned mlo = 0u, mhi = 0u;
;         if (!generic) {
;     ...
;             WL1(0) WL1(1) WL1(2) WL1(3) WL1(4) WL1(5) WL1(6) WL1(7) WL1(8) WL1(9) WL1(10) WL1(11) WL1(12) WL1(13) WL1(14) WL1(15)
;             WL1(16) WL1(17) WL1(18) WL1(19) WL1(20) WL1(21) WL1(22) WL1(23) WL1(24) WL1(25) WL1(26) WL1(27) WL1(28) WL1(29) WL1(30) WL1(31)
.Lrk3_top:
	s_add_i32 s98, s38, 1
	s_cmp_lt_u32 s98, s43
	s_cbranch_scc0 .Lrk3_one
	v_readlane_b32 s8, v2, s38
	v_readlane_b32 s98, v2, s98
	s_add_i32 s38, s38, 2
	v_cmp_gt_u32_e64 s[8:9], s8, v2
	v_cmp_gt_u32_e64 s[98:99], s98, v2
	s_cmp_lt_u32 s38, s43
	v_addc_co_u32_e64 v3, s[8:9], 0, v3, s[8:9]
	v_addc_co_u32_e64 v3, s[98:99], 0, v3, s[98:99]
	s_cbranch_scc1 .Lrk3_top
	s_branch .Lrk3_done
.Lrk3_one:
	v_readlane_b32 s8, v2, s38
	s_add_i32 s38, s38, 1
	s_nop 1
	v_cmp_gt_u32_e64 s[8:9], s8, v2
	s_nop 1
	v_addc_co_u32_e64 v3, s[8:9], 0, v3, s[8:9]
.Lrk3_done:
.LBB0_727:
	s_sub_i32 s38, 0x100, s42
	v_cmp_gt_u32_e64 s[8:9], s38, v3
	v_and_b32_e32 v25, 64, v224
	s_and_b64 s[8:9], vcc, s[8:9]
	v_add_u32_e32 v25, 64, v25
	v_xor_b32_e32 v26, 1, v224
	s_waitcnt lgkmcnt(0)
	v_cndmask_b32_e64 v5, -1, v2, s[8:9]
	s_nop 1
	v_min_u32_dpp v5, v5, v5 row_shr:1 row_mask:0xf bank_mask:0xf
	s_nop 1
	v_min_u32_dpp v5, v5, v5 row_shr:2 row_mask:0xf bank_mask:0xf
	s_nop 1
	v_min_u32_dpp v5, v5, v5 row_shr:4 row_mask:0xf bank_mask:0xf
	s_nop 1
	v_min_u32_dpp v5, v5, v5 row_shr:8 row_mask:0xf bank_mask:0xf
	s_nop 1
	v_min_u32_dpp v5, v5, v5 row_bcast:15 row_mask:0xa bank_mask:0xf
	s_nop 1
	v_min_u32_dpp v5, v5, v5 row_bcast:31 row_mask:0xc bank_mask:0xf
	s_nop 1
	v_readlane_b32 s8, v5, 63
	s_nop 1
	v_mov_b32_e32 v5, s8
	v_cmp_eq_u32_e64 s[8:9], v2, v5
	s_and_b64 s[8:9], vcc, s[8:9]
	s_nop 0
	v_cndmask_b32_e64 v2, 0, 1, s[8:9]
	v_cmp_ne_u32_e32 vcc, 0, v2
	s_bcnt1_i32_b64 s8, vcc
	s_ff1_i32_b64 s9, vcc
	s_cmp_lg_u64 vcc, 0
	s_cselect_b32 s9, s9, 0
	v_readlane_b32 s9, v3, s9
	s_sub_i32 s9, s38, s9
	s_cmp_ge_u32 s9, s8
	s_mov_b64 s[8:9], -1
	s_cbranch_scc0 .LBB0_729
	v_cmp_ge_u32_e32 vcc, v4, v5
	v_mov_b32_e32 v2, v0
	v_mov_b32_e32 v3, v0
	s_nop 3
	v_writelane_b32 v2, vcc_lo, 0
	v_writelane_b32 v3, vcc_hi, 0
	v_cmp_ge_u32_e32 vcc, v10, v5
	s_nop 3
	v_writelane_b32 v2, vcc_lo, 1
	v_writelane_b32 v3, vcc_hi, 1
	v_cmp_ge_u32_e32 vcc, v11, v5
	s_nop 3
	v_writelane_b32 v2, vcc_lo, 2
	v_writelane_b32 v3, vcc_hi, 2
	v_cmp_ge_u32_e32 vcc, v12, v5
	s_nop 3
	v_writelane_b32 v2, vcc_lo, 3
	v_writelane_b32 v3, vcc_hi, 3
	v_cmp_ge_u32_e32 vcc, v13, v5
	s_nop 3
	v_writelane_b32 v2, vcc_lo, 4
	v_writelane_b32 v3, vcc_hi, 4
	v_cmp_ge_u32_e32 vcc, v14, v5
	s_nop 3
	v_writelane_b32 v2, vcc_lo, 5
	v_writelane_b32 v3, vcc_hi, 5
	v_cmp_ge_u32_e32 vcc, v15, v5
	s_nop 3
	v_writelane_b32 v2, vcc_lo, 6
	v_writelane_b32 v3, vcc_hi, 6
	v_cmp_ge_u32_e32 vcc, v16, v5
	s_nop 3
	v_writelane_b32 v2, vcc_lo, 7
	v_writelane_b32 v3, vcc_hi, 7
	v_cmp_ge_u32_e32 vcc, v17, v5
	s_nop 3
	v_writelane_b32 v2, vcc_lo, 8
	v_writelane_b32 v3, vcc_hi, 8
	v_cmp_ge_u32_e32 vcc, v18, v5
	s_nop 3
	v_writelane_b32 v2, vcc_lo, 9
	v_writelane_b32 v3, vcc_hi, 9
	v_cmp_ge_u32_e32 vcc, v19, v5
	s_nop 3
	v_writelane_b32 v2, vcc_lo, 10
	v_writelane_b32 v3, vcc_hi, 10
	v_cmp_ge_u32_e32 vcc, v20, v5
	s_nop 3
	v_writelane_b32 v2, vcc_lo, 11
	v_writelane_b32 v3, vcc_hi, 11
	v_cmp_ge_u32_e32 vcc, v21, v5
	s_nop 3
	v_writelane_b32 v2, vcc_lo, 12
	v_writelane_b32 v3, vcc_hi, 12
	v_cmp_ge_u32_e32 vcc, v22, v5
	s_nop 3
	v_writelane_b32 v2, vcc_lo, 13
	v_writelane_b32 v3, vcc_hi, 13
	v_cmp_ge_u32_e32 vcc, v23, v5
	s_nop 3
	v_writelane_b32 v2, vcc_lo, 14
	v_writelane_b32 v3, vcc_hi, 14
	v_cmp_ge_u32_e32 vcc, v24, v5
	s_nop 3
	v_writelane_b32 v2, vcc_lo, 15
	v_writelane_b32 v3, vcc_hi, 15
	s_mov_b64 s[8:9], 0

; #define WL1(J) if constexpr (J < NJ) { const unsigned long long w_ = __ballot(key[J] >= tau); const unsigned wl_ = (unsigned)w_, wh_ = (unsigned)(w_ >> 32); \
;                 asm volatile("s_nop 3\n\tv_writelane_b32 %0, %2, " #J "\n\tv_writelane_b32 %1, %3, " #J : "+v"(mlo), "+v"(mhi) : "s"(wl_), "s"(wh_)); }
; template <int NJ>
; __device__ __forceinline__ void select_rows(const GAS float* sr0, GAS unsigned long long* mb0, LAS unsigned* hist, LAS unsigned* kbuf, int ntl, int lane) {
;     ...
;             for (unsigned i = 0; i < C; ++i) { const unsigned o = (unsigned)__builtin_amdgcn_readlane((int)mykey, (int)i); cgt += (o > mykey) ? 1u : 0u; }
;             unsigned t = (have && cgt < rem) ? mykey : 0xffffffffu;
; #pragma unroll
;             for (int o = 1; o < 64; o <<= 1) t = min(t, (unsigned)__shfl_xor((int)t, o));
;             tau = t;
;             const unsigned long long eqm = __ballot(have && mykey == tau);
;             cnteq = (unsigned)__popcll(eqm);
;             remf = rem - (unsigned)__builtin_amdgcn_readlane((int)cgt, eqm ? (int)__builtin_ctzll(eqm) : 0);
;             generic = cnteq > remf;
;         }
;         unsigned mlo = 0u, mhi = 0u;
;         if (!generic) {
;     ...
;             WL1(0) WL1(1) WL1(2) WL1(3) WL1(4) WL1(5) WL1(6) WL1(7) WL1(8) WL1(9) WL1(10) WL1(11) WL1(12) WL1(13) WL1(14) WL1(15)
;             WL1(16) WL1(17) WL1(18) WL1(19) WL1(20) WL1(21) WL1(22) WL1(23) WL1(24) WL1(25) WL1(26) WL1(27) WL1(28) WL1(29) WL1(30) WL1(31)
.Lrk4_top:
	s_add_i32 s98, s48, 1
	s_cmp_lt_u32 s98, s53
	s_cbranch_scc0 .Lrk4_one
	v_readlane_b32 s8, v2, s48
	v_readlane_b32 s98, v2, s98
	s_add_i32 s48, s48, 2
	v_cmp_gt_u32_e64 s[8:9], s8, v2
	v_cmp_gt_u32_e64 s[98:99], s98, v2
	s_cmp_lt_u32 s48, s53
	v_addc_co_u32_e64 v3, s[8:9], 0, v3, s[8:9]
	v_addc_co_u32_e64 v3, s[98:99], 0, v3, s[98:99]
	s_cbranch_scc1 .Lrk4_top
	s_branch .Lrk4_done
.Lrk4_one:
	v_readlane_b32 s8, v2, s48
	s_add_i32 s48, s48, 1
	s_nop 1
	v_cmp_gt_u32_e64 s[8:9], s8, v2
	s_nop 1
	v_addc_co_u32_e64 v3, s[8:9], 0, v3, s[8:9]
.Lrk4_done:
.LBB0_782:
	s_sub_i32 s48, 0x100, s52
	v_cmp_gt_u32_e64 s[8:9], s48, v3
	v_and_b32_e32 v17, 64, v224
	s_and_b64 s[8:9], vcc, s[8:9]
	v_add_u32_e32 v17, 64, v17
	v_xor_b32_e32 v18, 1, v224
	s_waitcnt lgkmcnt(0)
	v_cndmask_b32_e64 v5, -1, v2, s[8:9]
	s_nop 1
	v_min_u32_dpp v5, v5, v5 row_shr:1 row_mask:0xf bank_mask:0xf
	s_nop 1
	v_min_u32_dpp v5, v5, v5 row_shr:2 row_mask:0xf bank_mask:0xf
	s_nop 1
	v_min_u32_dpp v5, v5, v5 row_shr:4 row_mask:0xf bank_mask:0xf
	s_nop 1
	v_min_u32_dpp v5, v5, v5 row_shr:8 row_mask:0xf bank_mask:0xf
	s_nop 1
	v_min_u32_dpp v5, v5, v5 row_bcast:15 row_mask:0xa bank_mask:0xf
	s_nop 1
	v_min_u32_dpp v5, v5, v5 row_bcast:31 row_mask:0xc bank_mask:0xf
	s_nop 1
	v_readlane_b32 s8, v5, 63
	s_nop 1
	v_mov_b32_e32 v5, s8
	v_cmp_eq_u32_e64 s[8:9], v2, v5
	s_and_b64 s[8:9], vcc, s[8:9]
	s_nop 0
	v_cndmask_b32_e64 v2, 0, 1, s[8:9]
	v_cmp_ne_u32_e32 vcc, 0, v2
	s_bcnt1_i32_b64 s8, vcc
	s_ff1_i32_b64 s9, vcc
	s_cmp_lg_u64 vcc, 0
	s_cselect_b32 s9, s9, 0
	v_readlane_b32 s9, v3, s9
	s_sub_i32 s9, s48, s9
	s_cmp_ge_u32 s9, s8
	s_mov_b64 s[8:9], -1
	s_cbranch_scc0 .LBB0_784
	v_cmp_ge_u32_e32 vcc, v4, v5
	v_mov_b32_e32 v2, v0
	v_mov_b32_e32 v3, v0
	s_nop 3
	v_writelane_b32 v2, vcc_lo, 0
	v_writelane_b32 v3, vcc_hi, 0
	v_cmp_ge_u32_e32 vcc, v10, v5
	s_nop 3
	v_writelane_b32 v2, vcc_lo, 1
	v_writelane_b32 v3, vcc_hi, 1
	v_cmp_ge_u32_e32 vcc, v11, v5
	s_nop 3
	v_writelane_b32 v2, vcc_lo, 2
	v_writelane_b32 v3, vcc_hi, 2
	v_cmp_ge_u32_e32 vcc, v12, v5
	s_nop 3
	v_writelane_b32 v2, vcc_lo, 3
	v_writelane_b32 v3, vcc_hi, 3
	v_cmp_ge_u32_e32 vcc, v13, v5
	s_nop 3
	v_writelane_b32 v2, vcc_lo, 4
	v_writelane_b32 v3, vcc_hi, 4
	v_cmp_ge_u32_e32 vcc, v14, v5
	s_nop 3
	v_writelane_b32 v2, vcc_lo, 5
	v_writelane_b32 v3, vcc_hi, 5
	v_cmp_ge_u32_e32 vcc, v15, v5
	s_nop 3
	v_writelane_b32 v2, vcc_lo, 6
	v_writelane_b32 v3, vcc_hi, 6
	v_cmp_ge_u32_e32 vcc, v16, v5
	s_nop 3
	v_writelane_b32 v2, vcc_lo, 7
	v_writelane_b32 v3, vcc_hi, 7
	s_mov_b64 s[8:9], 0
